# GEMM1 gate epilogue: dead per-block address arithmetic (fed the removed lower-bound loads) deleted, 214 VALU lines
# baseline (speedup 1.0000x reference)
.LBB0_149:
	s_or_b64 exec, exec, s[0:1]
	v_add_u32_e32 v134, 16, v131
	v_ashrrev_i32_e32 v135, 11, v134
	v_cmp_lt_u32_e32 vcc, s24, v134
	v_cmp_ne_u32_e64 s[0:1], 4, v135
	v_and_b32_e32 v132, 0x7ff, v134
	s_and_b64 s[46:47], vcc, s[0:1]
	s_and_saveexec_b64 s[0:1], s[46:47]
	s_xor_b64 s[0:1], exec, s[0:1]
	s_cbranch_execz .LBB0_153
	v_cmp_ne_u32_e32 vcc, 3, v135
	s_and_saveexec_b64 s[2:3], vcc
	s_cbranch_execz .LBB0_152
	v_mov_b64_e32 v[136:137], v[148:149]
	v_mov_b64_e32 v[138:139], v[150:151]
	v_mul_f32_e32 v120, 0xbfb8aa3b, v120
	v_exp_f32_e32 v120, v120
	v_mul_f32_e32 v121, 0xbfb8aa3b, v121
	v_exp_f32_e32 v121, v121
	v_mul_f32_e32 v122, 0xbfb8aa3b, v122
	v_exp_f32_e32 v122, v122
	v_mul_f32_e32 v123, 0xbfb8aa3b, v123
	v_exp_f32_e32 v123, v123
	v_add_f32_e32 v120, 1.0, v120
	v_rcp_f32_e32 v120, v120
	v_add_f32_e32 v121, 1.0, v121
	v_rcp_f32_e32 v121, v121
	v_add_f32_e32 v122, 1.0, v122
	v_rcp_f32_e32 v122, v122
	v_add_f32_e32 v123, 1.0, v123
	v_rcp_f32_e32 v123, v123
	v_sub_f32_e32 v128, 1.0, v136
	v_fma_f32 v120, v120, v128, v136
	v_sub_f32_e32 v128, 1.0, v137
	v_fma_f32 v121, v121, v128, v137
	v_sub_f32_e32 v128, 1.0, v138
	v_fma_f32 v122, v122, v128, v138
	v_sub_f32_e32 v128, 1.0, v139
	v_fmac_f32_e32 v139, v123, v128
	v_log_f32_e32 v120, v120
	v_log_f32_e32 v121, v121
	v_log_f32_e32 v122, v122
	v_log_f32_e32 v123, v139
	v_pk_mul_f32 v[120:121], v[120:121], s[96:97] op_sel_hi:[1,0]
	v_pk_mul_f32 v[122:123], v[122:123], s[96:97] op_sel_hi:[1,0]

.LBB0_155:
	s_or_b64 exec, exec, s[0:1]
	v_cvt_pk_bf16_f32 v138, v120, v121
	v_add_u32_e32 v120, s6, v215
	v_add_u32_e32 v128, s48, v214
	v_cvt_pk_bf16_f32 v139, v122, v123
	v_ashrrev_i32_e32 v122, 11, v120
	v_ashrrev_i32_e32 v129, 31, v128
	v_cvt_pk_bf16_f32 v136, v124, v125
	v_and_b32_e32 v124, 0x7ff, v120
	v_mul_hi_i32_i24_e32 v121, 0x4400, v122
	v_mul_i32_i24_e32 v120, 0x4400, v122
	v_lshl_add_u64 v[122:123], v[120:121], 0, v[128:129]
	v_lshlrev_b64 v[122:123], 12, v[122:123]
	v_cvt_pk_bf16_f32 v137, v126, v127
	v_lshl_add_u64 v[122:123], s[86:87], 0, v[122:123]
	v_lshlrev_b32_e32 v176, 1, v124
	v_permlane16_swap_b32_e32 v136, v138
	v_permlane16_swap_b32_e32 v137, v139
	v_lshl_add_u64 v[122:123], v[122:123], 0, v[176:177]
	s_add_i32 s6, s6, 32
	global_store_dwordx4 v[122:123], v[136:139], off
	v_add_u32_e32 v123, s6, v213
	v_ashrrev_i32_e32 v126, 11, v123
	v_cmp_lt_u32_e32 vcc, s24, v123
	v_cmp_ne_u32_e64 s[0:1], 4, v126
	v_and_b32_e32 v122, 0x7ff, v123
	s_and_b64 s[48:49], vcc, s[0:1]
	s_and_saveexec_b64 s[0:1], s[48:49]
	s_xor_b64 s[0:1], exec, s[0:1]
	s_cbranch_execz .LBB0_159
	v_cmp_ne_u32_e32 vcc, 3, v126
	s_and_saveexec_b64 s[2:3], vcc
	s_cbranch_execz .LBB0_158
	v_mov_b64_e32 v[136:137], v[152:153]
	v_mov_b64_e32 v[138:139], v[154:155]
	v_mul_f32_e32 v116, 0xbfb8aa3b, v116
	v_exp_f32_e32 v116, v116
	v_mul_f32_e32 v117, 0xbfb8aa3b, v117
	v_exp_f32_e32 v117, v117
	v_mul_f32_e32 v118, 0xbfb8aa3b, v118
	v_exp_f32_e32 v118, v118
	v_mul_f32_e32 v119, 0xbfb8aa3b, v119
	v_exp_f32_e32 v119, v119
	v_add_f32_e32 v116, 1.0, v116
	v_rcp_f32_e32 v116, v116
	v_add_f32_e32 v117, 1.0, v117
	v_rcp_f32_e32 v117, v117
	v_add_f32_e32 v118, 1.0, v118
	v_rcp_f32_e32 v118, v118
	v_add_f32_e32 v119, 1.0, v119
	v_rcp_f32_e32 v119, v119
	v_sub_f32_e32 v124, 1.0, v136
	v_fma_f32 v116, v116, v124, v136
	v_sub_f32_e32 v124, 1.0, v137
	v_fma_f32 v117, v117, v124, v137
	v_sub_f32_e32 v124, 1.0, v138
	v_fma_f32 v118, v118, v124, v138
	v_sub_f32_e32 v124, 1.0, v139
	v_fmac_f32_e32 v139, v119, v124
	v_log_f32_e32 v116, v116
	v_log_f32_e32 v117, v117
	v_log_f32_e32 v118, v118
	v_log_f32_e32 v119, v139
	v_pk_mul_f32 v[116:117], v[116:117], s[96:97] op_sel_hi:[1,0]
	v_pk_mul_f32 v[118:119], v[118:119], s[96:97] op_sel_hi:[1,0]

.LBB0_161:
	s_or_b64 exec, exec, s[0:1]
	v_add_u32_e32 v125, 16, v123
	v_ashrrev_i32_e32 v127, 11, v125
	v_cmp_lt_u32_e32 vcc, s24, v125
	v_cmp_ne_u32_e64 s[0:1], 4, v127
	v_and_b32_e32 v124, 0x7ff, v125
	s_and_b64 s[0:1], vcc, s[0:1]
	s_and_saveexec_b64 s[2:3], s[0:1]
	s_xor_b64 s[2:3], exec, s[2:3]
	s_cbranch_execz .LBB0_165
	v_cmp_ne_u32_e32 vcc, 3, v127
	s_and_saveexec_b64 s[8:9], vcc
	s_cbranch_execz .LBB0_164
	v_mov_b64_e32 v[136:137], v[156:157]
	v_mov_b64_e32 v[138:139], v[158:159]
	v_mul_f32_e32 v112, 0xbfb8aa3b, v112
	v_exp_f32_e32 v112, v112
	v_mul_f32_e32 v113, 0xbfb8aa3b, v113
	v_exp_f32_e32 v113, v113
	v_mul_f32_e32 v114, 0xbfb8aa3b, v114
	v_exp_f32_e32 v114, v114
	v_mul_f32_e32 v115, 0xbfb8aa3b, v115
	v_exp_f32_e32 v115, v115
	v_add_f32_e32 v112, 1.0, v112
	v_rcp_f32_e32 v112, v112
	v_add_f32_e32 v113, 1.0, v113
	v_rcp_f32_e32 v113, v113
	v_add_f32_e32 v114, 1.0, v114
	v_rcp_f32_e32 v114, v114
	v_add_f32_e32 v115, 1.0, v115
	v_rcp_f32_e32 v115, v115
	v_sub_f32_e32 v140, 1.0, v136
	v_fma_f32 v112, v112, v140, v136
	v_sub_f32_e32 v136, 1.0, v137
	v_fma_f32 v113, v113, v136, v137
	v_sub_f32_e32 v136, 1.0, v138
	v_fma_f32 v114, v114, v136, v138
	v_sub_f32_e32 v136, 1.0, v139
	v_fmac_f32_e32 v139, v115, v136
	v_log_f32_e32 v112, v112
	v_log_f32_e32 v113, v113
	v_log_f32_e32 v114, v114
	v_log_f32_e32 v115, v139
	v_pk_mul_f32 v[112:113], v[112:113], s[96:97] op_sel_hi:[1,0]
	v_pk_mul_f32 v[114:115], v[114:115], s[96:97] op_sel_hi:[1,0]

.LBB0_167:
	s_or_b64 exec, exec, s[2:3]
	v_cvt_pk_bf16_f32 v138, v112, v113
	v_add_u32_e32 v112, s6, v215
	v_cvt_pk_bf16_f32 v139, v114, v115
	v_ashrrev_i32_e32 v114, 11, v112
	v_cvt_pk_bf16_f32 v137, v118, v119
	v_and_b32_e32 v118, 0x7ff, v112
	v_mul_hi_i32_i24_e32 v113, 0x4400, v114
	v_mul_i32_i24_e32 v112, 0x4400, v114
	v_lshl_add_u64 v[114:115], v[112:113], 0, v[128:129]
	v_lshlrev_b64 v[114:115], 12, v[114:115]
	v_cvt_pk_bf16_f32 v136, v116, v117
	v_lshl_add_u64 v[116:117], s[86:87], 0, v[114:115]
	v_lshlrev_b32_e32 v114, 1, v118
	v_mov_b32_e32 v115, v177
	v_permlane16_swap_b32_e32 v136, v138
	v_permlane16_swap_b32_e32 v137, v139
	v_lshl_add_u64 v[116:117], v[116:117], 0, v[114:115]
	global_store_dwordx4 v[116:117], v[136:139], off
	s_and_saveexec_b64 s[2:3], s[44:45]
	s_xor_b64 s[2:3], exec, s[2:3]
	s_cbranch_execz .LBB0_175
	v_cmp_ne_u32_e32 vcc, 3, v133
	s_and_saveexec_b64 s[8:9], vcc
	s_cbranch_execz .LBB0_170
	v_mov_b64_e32 v[116:117], v[144:145]
	v_mov_b64_e32 v[118:119], v[146:147]
	v_mul_f32_e32 v108, 0xbfb8aa3b, v108
	v_exp_f32_e32 v108, v108
	v_mul_f32_e32 v109, 0xbfb8aa3b, v109
	v_exp_f32_e32 v109, v109
	v_mul_f32_e32 v110, 0xbfb8aa3b, v110
	v_exp_f32_e32 v110, v110
	v_mul_f32_e32 v111, 0xbfb8aa3b, v111
	v_exp_f32_e32 v111, v111
	v_add_f32_e32 v108, 1.0, v108
	v_rcp_f32_e32 v108, v108
	v_add_f32_e32 v109, 1.0, v109
	v_rcp_f32_e32 v109, v109
	v_add_f32_e32 v110, 1.0, v110
	v_rcp_f32_e32 v110, v110
	v_add_f32_e32 v111, 1.0, v111
	v_rcp_f32_e32 v111, v111
	v_sub_f32_e32 v115, 1.0, v116
	v_fma_f32 v108, v108, v115, v116
	v_sub_f32_e32 v115, 1.0, v117
	v_fma_f32 v109, v109, v115, v117
	v_sub_f32_e32 v115, 1.0, v118
	v_fma_f32 v110, v110, v115, v118
	v_sub_f32_e32 v115, 1.0, v119
	v_fmac_f32_e32 v119, v111, v115
	v_log_f32_e32 v108, v108
	v_log_f32_e32 v109, v109
	v_log_f32_e32 v110, v110
	v_log_f32_e32 v111, v119
	v_pk_mul_f32 v[108:109], v[108:109], s[96:97] op_sel_hi:[1,0]
	v_pk_mul_f32 v[110:111], v[110:111], s[96:97] op_sel_hi:[1,0]

.LBB0_172:
	v_cmp_ne_u32_e32 vcc, 3, v135
	s_and_saveexec_b64 s[8:9], vcc
	s_cbranch_execz .LBB0_174
	v_mov_b64_e32 v[116:117], v[148:149]
	v_mov_b64_e32 v[118:119], v[150:151]
	v_mul_f32_e32 v104, 0xbfb8aa3b, v104
	v_exp_f32_e32 v104, v104
	v_mul_f32_e32 v105, 0xbfb8aa3b, v105
	v_exp_f32_e32 v105, v105
	v_mul_f32_e32 v106, 0xbfb8aa3b, v106
	v_exp_f32_e32 v106, v106
	v_mul_f32_e32 v107, 0xbfb8aa3b, v107
	v_exp_f32_e32 v107, v107
	v_add_f32_e32 v104, 1.0, v104
	v_rcp_f32_e32 v104, v104
	v_add_f32_e32 v105, 1.0, v105
	v_rcp_f32_e32 v105, v105
	v_add_f32_e32 v106, 1.0, v106
	v_rcp_f32_e32 v106, v106
	v_add_f32_e32 v107, 1.0, v107
	v_rcp_f32_e32 v107, v107
	v_sub_f32_e32 v115, 1.0, v116
	v_fma_f32 v104, v104, v115, v116
	v_sub_f32_e32 v115, 1.0, v117
	v_fma_f32 v105, v105, v115, v117
	v_sub_f32_e32 v115, 1.0, v118
	v_fma_f32 v106, v106, v115, v118
	v_sub_f32_e32 v115, 1.0, v119
	v_fmac_f32_e32 v119, v107, v115
	v_log_f32_e32 v104, v104
	v_log_f32_e32 v105, v105
	v_log_f32_e32 v106, v106
	v_log_f32_e32 v107, v119
	v_pk_mul_f32 v[104:105], v[104:105], s[96:97] op_sel_hi:[1,0]
	v_pk_mul_f32 v[106:107], v[106:107], s[96:97] op_sel_hi:[1,0]

.LBB0_179:
	s_or_b64 exec, exec, s[2:3]
	v_add_u32_e32 v116, 16, v128
	v_ashrrev_i32_e32 v117, 31, v116
	v_cvt_pk_bf16_f32 v138, v104, v105
	v_lshl_add_u64 v[104:105], v[120:121], 0, v[116:117]
	v_lshlrev_b64 v[104:105], 12, v[104:105]
	v_cvt_pk_bf16_f32 v137, v110, v111
	v_cvt_pk_bf16_f32 v136, v108, v109
	v_cvt_pk_bf16_f32 v139, v106, v107
	v_lshl_add_u64 v[104:105], s[86:87], 0, v[104:105]
	v_permlane16_swap_b32_e32 v136, v138
	v_permlane16_swap_b32_e32 v137, v139
	v_lshl_add_u64 v[104:105], v[104:105], 0, v[176:177]
	global_store_dwordx4 v[104:105], v[136:139], off
	s_and_saveexec_b64 s[2:3], s[48:49]
	s_xor_b64 s[2:3], exec, s[2:3]
	s_cbranch_execz .LBB0_187
	v_cmp_ne_u32_e32 vcc, 3, v126
	s_and_saveexec_b64 s[8:9], vcc
	s_cbranch_execz .LBB0_182
	v_mov_b64_e32 v[104:105], v[152:153]
	v_mov_b64_e32 v[106:107], v[154:155]
	v_mul_f32_e32 v100, 0xbfb8aa3b, v100
	v_exp_f32_e32 v100, v100
	v_mul_f32_e32 v101, 0xbfb8aa3b, v101
	v_exp_f32_e32 v101, v101
	v_mul_f32_e32 v102, 0xbfb8aa3b, v102
	v_exp_f32_e32 v102, v102
	v_mul_f32_e32 v103, 0xbfb8aa3b, v103
	v_exp_f32_e32 v103, v103
	v_add_f32_e32 v100, 1.0, v100
	v_rcp_f32_e32 v100, v100
	v_add_f32_e32 v101, 1.0, v101
	v_rcp_f32_e32 v101, v101
	v_add_f32_e32 v102, 1.0, v102
	v_rcp_f32_e32 v102, v102
	v_add_f32_e32 v103, 1.0, v103
	v_rcp_f32_e32 v103, v103
	v_sub_f32_e32 v108, 1.0, v104
	v_fma_f32 v100, v100, v108, v104
	v_sub_f32_e32 v104, 1.0, v105
	v_fma_f32 v101, v101, v104, v105
	v_sub_f32_e32 v104, 1.0, v106
	v_fma_f32 v102, v102, v104, v106
	v_sub_f32_e32 v104, 1.0, v107
	v_fmac_f32_e32 v107, v103, v104
	v_log_f32_e32 v100, v100
	v_log_f32_e32 v101, v101
	v_log_f32_e32 v102, v102
	v_log_f32_e32 v103, v107
	v_pk_mul_f32 v[100:101], v[100:101], s[96:97] op_sel_hi:[1,0]
	v_pk_mul_f32 v[102:103], v[102:103], s[96:97] op_sel_hi:[1,0]

.LBB0_184:
	v_cmp_ne_u32_e32 vcc, 3, v127
	s_and_saveexec_b64 s[8:9], vcc
	s_cbranch_execz .LBB0_186
	v_mov_b64_e32 v[104:105], v[156:157]
	v_mov_b64_e32 v[106:107], v[158:159]
	v_mul_f32_e32 v96, 0xbfb8aa3b, v96
	v_exp_f32_e32 v96, v96
	v_mul_f32_e32 v97, 0xbfb8aa3b, v97
	v_exp_f32_e32 v97, v97
	v_mul_f32_e32 v98, 0xbfb8aa3b, v98
	v_exp_f32_e32 v98, v98
	v_mul_f32_e32 v99, 0xbfb8aa3b, v99
	v_exp_f32_e32 v99, v99
	v_add_f32_e32 v96, 1.0, v96
	v_rcp_f32_e32 v96, v96
	v_add_f32_e32 v97, 1.0, v97
	v_rcp_f32_e32 v97, v97
	v_add_f32_e32 v98, 1.0, v98
	v_rcp_f32_e32 v98, v98
	v_add_f32_e32 v99, 1.0, v99
	v_rcp_f32_e32 v99, v99
	v_sub_f32_e32 v108, 1.0, v104
	v_fma_f32 v96, v96, v108, v104
	v_sub_f32_e32 v104, 1.0, v105
	v_fma_f32 v97, v97, v104, v105
	v_sub_f32_e32 v104, 1.0, v106
	v_fma_f32 v98, v98, v104, v106
	v_sub_f32_e32 v104, 1.0, v107
	v_fmac_f32_e32 v107, v99, v104
	v_log_f32_e32 v96, v96
	v_log_f32_e32 v97, v97
	v_log_f32_e32 v98, v98
	v_log_f32_e32 v99, v107
	v_pk_mul_f32 v[96:97], v[96:97], s[96:97] op_sel_hi:[1,0]
	v_pk_mul_f32 v[98:99], v[98:99], s[96:97] op_sel_hi:[1,0]

.LBB0_191:
	s_or_b64 exec, exec, s[2:3]
	v_cvt_pk_bf16_f32 v104, v96, v97
	v_lshl_add_u64 v[96:97], v[112:113], 0, v[116:117]
	v_lshlrev_b64 v[96:97], 12, v[96:97]
	v_cvt_pk_bf16_f32 v103, v102, v103
	v_cvt_pk_bf16_f32 v102, v100, v101
	v_cvt_pk_bf16_f32 v105, v98, v99
	v_lshl_add_u64 v[96:97], s[86:87], 0, v[96:97]
	v_mov_b32_e32 v115, v177
	v_permlane16_swap_b32_e32 v102, v104
	v_permlane16_swap_b32_e32 v103, v105
	v_lshl_add_u64 v[96:97], v[96:97], 0, v[114:115]
	global_store_dwordx4 v[96:97], v[102:105], off
	s_and_saveexec_b64 s[2:3], s[44:45]
	s_xor_b64 s[2:3], exec, s[2:3]
	s_cbranch_execz .LBB0_199
	v_cmp_ne_u32_e32 vcc, 3, v133
	s_and_saveexec_b64 s[8:9], vcc
	s_cbranch_execz .LBB0_194
	v_mov_b64_e32 v[96:97], v[144:145]
	v_mov_b64_e32 v[98:99], v[146:147]
	v_mul_f32_e32 v92, 0xbfb8aa3b, v92
	v_exp_f32_e32 v92, v92
	v_mul_f32_e32 v93, 0xbfb8aa3b, v93
	v_exp_f32_e32 v93, v93
	v_mul_f32_e32 v94, 0xbfb8aa3b, v94
	v_exp_f32_e32 v94, v94
	v_mul_f32_e32 v95, 0xbfb8aa3b, v95
	v_exp_f32_e32 v95, v95
	v_add_f32_e32 v92, 1.0, v92
	v_rcp_f32_e32 v92, v92
	v_add_f32_e32 v93, 1.0, v93
	v_rcp_f32_e32 v93, v93
	v_add_f32_e32 v94, 1.0, v94
	v_rcp_f32_e32 v94, v94
	v_add_f32_e32 v95, 1.0, v95
	v_rcp_f32_e32 v95, v95
	v_sub_f32_e32 v100, 1.0, v96
	v_fma_f32 v92, v92, v100, v96
	v_sub_f32_e32 v96, 1.0, v97
	v_fma_f32 v93, v93, v96, v97
	v_sub_f32_e32 v96, 1.0, v98
	v_fma_f32 v94, v94, v96, v98
	v_sub_f32_e32 v96, 1.0, v99
	v_fmac_f32_e32 v99, v95, v96
	v_log_f32_e32 v92, v92
	v_log_f32_e32 v93, v93
	v_log_f32_e32 v94, v94
	v_log_f32_e32 v95, v99
	v_pk_mul_f32 v[92:93], v[92:93], s[96:97] op_sel_hi:[1,0]
	v_pk_mul_f32 v[94:95], v[94:95], s[96:97] op_sel_hi:[1,0]

.LBB0_196:
	v_cmp_ne_u32_e32 vcc, 3, v135
	s_and_saveexec_b64 s[8:9], vcc
	s_cbranch_execz .LBB0_198
	v_mov_b64_e32 v[96:97], v[148:149]
	v_mov_b64_e32 v[98:99], v[150:151]
	v_mul_f32_e32 v88, 0xbfb8aa3b, v88
	v_exp_f32_e32 v88, v88
	v_mul_f32_e32 v89, 0xbfb8aa3b, v89
	v_exp_f32_e32 v89, v89
	v_mul_f32_e32 v90, 0xbfb8aa3b, v90
	v_exp_f32_e32 v90, v90
	v_mul_f32_e32 v91, 0xbfb8aa3b, v91
	v_exp_f32_e32 v91, v91
	v_add_f32_e32 v88, 1.0, v88
	v_rcp_f32_e32 v88, v88
	v_add_f32_e32 v89, 1.0, v89
	v_rcp_f32_e32 v89, v89
	v_add_f32_e32 v90, 1.0, v90
	v_rcp_f32_e32 v90, v90
	v_add_f32_e32 v91, 1.0, v91
	v_rcp_f32_e32 v91, v91
	v_sub_f32_e32 v100, 1.0, v96
	v_fma_f32 v88, v88, v100, v96
	v_sub_f32_e32 v96, 1.0, v97
	v_fma_f32 v89, v89, v96, v97
	v_sub_f32_e32 v96, 1.0, v98
	v_fma_f32 v90, v90, v96, v98
	v_sub_f32_e32 v96, 1.0, v99
	v_fmac_f32_e32 v99, v91, v96
	v_log_f32_e32 v88, v88
	v_log_f32_e32 v89, v89
	v_log_f32_e32 v90, v90
	v_log_f32_e32 v91, v99
	v_pk_mul_f32 v[88:89], v[88:89], s[96:97] op_sel_hi:[1,0]
	v_pk_mul_f32 v[90:91], v[90:91], s[96:97] op_sel_hi:[1,0]

.LBB0_203:
	s_or_b64 exec, exec, s[2:3]
	v_add_u32_e32 v96, 32, v128
	v_ashrrev_i32_e32 v97, 31, v96
	v_cvt_pk_bf16_f32 v100, v88, v89
	v_lshl_add_u64 v[88:89], v[120:121], 0, v[96:97]
	v_lshlrev_b64 v[88:89], 12, v[88:89]
	v_cvt_pk_bf16_f32 v99, v94, v95
	v_cvt_pk_bf16_f32 v98, v92, v93
	v_cvt_pk_bf16_f32 v101, v90, v91
	v_lshl_add_u64 v[88:89], s[86:87], 0, v[88:89]
	v_permlane16_swap_b32_e32 v98, v100
	v_permlane16_swap_b32_e32 v99, v101
	v_lshl_add_u64 v[88:89], v[88:89], 0, v[176:177]
	global_store_dwordx4 v[88:89], v[98:101], off
	s_and_saveexec_b64 s[2:3], s[48:49]
	s_xor_b64 s[2:3], exec, s[2:3]
	s_cbranch_execz .LBB0_211
	v_cmp_ne_u32_e32 vcc, 3, v126
	s_and_saveexec_b64 s[8:9], vcc
	s_cbranch_execz .LBB0_206
	v_mov_b64_e32 v[88:89], v[152:153]
	v_mov_b64_e32 v[90:91], v[154:155]
	v_mul_f32_e32 v84, 0xbfb8aa3b, v84
	v_exp_f32_e32 v84, v84
	v_mul_f32_e32 v85, 0xbfb8aa3b, v85
	v_exp_f32_e32 v85, v85
	v_mul_f32_e32 v86, 0xbfb8aa3b, v86
	v_exp_f32_e32 v86, v86
	v_mul_f32_e32 v87, 0xbfb8aa3b, v87
	v_exp_f32_e32 v87, v87
	v_add_f32_e32 v84, 1.0, v84
	v_rcp_f32_e32 v84, v84
	v_add_f32_e32 v85, 1.0, v85
	v_rcp_f32_e32 v85, v85
	v_add_f32_e32 v86, 1.0, v86
	v_rcp_f32_e32 v86, v86
	v_add_f32_e32 v87, 1.0, v87
	v_rcp_f32_e32 v87, v87
	v_sub_f32_e32 v92, 1.0, v88
	v_fma_f32 v84, v84, v92, v88
	v_sub_f32_e32 v88, 1.0, v89
	v_fma_f32 v85, v85, v88, v89
	v_sub_f32_e32 v88, 1.0, v90
	v_fma_f32 v86, v86, v88, v90
	v_sub_f32_e32 v88, 1.0, v91
	v_fmac_f32_e32 v91, v87, v88
	v_log_f32_e32 v84, v84
	v_log_f32_e32 v85, v85
	v_log_f32_e32 v86, v86
	v_log_f32_e32 v87, v91
	v_pk_mul_f32 v[84:85], v[84:85], s[96:97] op_sel_hi:[1,0]
	v_pk_mul_f32 v[86:87], v[86:87], s[96:97] op_sel_hi:[1,0]

.LBB0_208:
	v_cmp_ne_u32_e32 vcc, 3, v127
	s_and_saveexec_b64 s[8:9], vcc
	s_cbranch_execz .LBB0_210
	v_mov_b64_e32 v[88:89], v[156:157]
	v_mov_b64_e32 v[90:91], v[158:159]
	v_mul_f32_e32 v80, 0xbfb8aa3b, v80
	v_exp_f32_e32 v80, v80
	v_mul_f32_e32 v81, 0xbfb8aa3b, v81
	v_exp_f32_e32 v81, v81
	v_mul_f32_e32 v82, 0xbfb8aa3b, v82
	v_exp_f32_e32 v82, v82
	v_mul_f32_e32 v83, 0xbfb8aa3b, v83
	v_exp_f32_e32 v83, v83
	v_add_f32_e32 v80, 1.0, v80
	v_rcp_f32_e32 v80, v80
	v_add_f32_e32 v81, 1.0, v81
	v_rcp_f32_e32 v81, v81
	v_add_f32_e32 v82, 1.0, v82
	v_rcp_f32_e32 v82, v82
	v_add_f32_e32 v83, 1.0, v83
	v_rcp_f32_e32 v83, v83
	v_sub_f32_e32 v92, 1.0, v88
	v_fma_f32 v80, v80, v92, v88
	v_sub_f32_e32 v88, 1.0, v89
	v_fma_f32 v81, v81, v88, v89
	v_sub_f32_e32 v88, 1.0, v90
	v_fma_f32 v82, v82, v88, v90
	v_sub_f32_e32 v88, 1.0, v91
	v_fmac_f32_e32 v91, v83, v88
	v_log_f32_e32 v80, v80
	v_log_f32_e32 v81, v81
	v_log_f32_e32 v82, v82
	v_log_f32_e32 v83, v91
	v_pk_mul_f32 v[80:81], v[80:81], s[96:97] op_sel_hi:[1,0]
	v_pk_mul_f32 v[82:83], v[82:83], s[96:97] op_sel_hi:[1,0]

.LBB0_215:
	s_or_b64 exec, exec, s[2:3]
	v_cvt_pk_bf16_f32 v88, v80, v81
	v_lshl_add_u64 v[80:81], v[112:113], 0, v[96:97]
	v_lshlrev_b64 v[80:81], 12, v[80:81]
	v_cvt_pk_bf16_f32 v87, v86, v87
	v_cvt_pk_bf16_f32 v86, v84, v85
	v_cvt_pk_bf16_f32 v89, v82, v83
	v_lshl_add_u64 v[80:81], s[86:87], 0, v[80:81]
	v_mov_b32_e32 v115, v177
	v_permlane16_swap_b32_e32 v86, v88
	v_permlane16_swap_b32_e32 v87, v89
	v_lshl_add_u64 v[80:81], v[80:81], 0, v[114:115]
	global_store_dwordx4 v[80:81], v[86:89], off
	s_and_saveexec_b64 s[2:3], s[44:45]
	s_xor_b64 s[2:3], exec, s[2:3]
	s_cbranch_execz .LBB0_223
	v_cmp_ne_u32_e32 vcc, 3, v133
	s_and_saveexec_b64 s[8:9], vcc
	s_cbranch_execz .LBB0_218
	v_mov_b64_e32 v[80:81], v[144:145]
	v_mov_b64_e32 v[82:83], v[146:147]
	v_mul_f32_e32 v76, 0xbfb8aa3b, v76
	v_exp_f32_e32 v76, v76
	v_mul_f32_e32 v77, 0xbfb8aa3b, v77
	v_exp_f32_e32 v77, v77
	v_mul_f32_e32 v78, 0xbfb8aa3b, v78
	v_exp_f32_e32 v78, v78
	v_mul_f32_e32 v79, 0xbfb8aa3b, v79
	v_exp_f32_e32 v79, v79
	v_add_f32_e32 v76, 1.0, v76
	v_rcp_f32_e32 v76, v76
	v_add_f32_e32 v77, 1.0, v77
	v_rcp_f32_e32 v77, v77
	v_add_f32_e32 v78, 1.0, v78
	v_rcp_f32_e32 v78, v78
	v_add_f32_e32 v79, 1.0, v79
	v_rcp_f32_e32 v79, v79
	v_sub_f32_e32 v84, 1.0, v80
	v_fma_f32 v76, v76, v84, v80
	v_sub_f32_e32 v80, 1.0, v81
	v_fma_f32 v77, v77, v80, v81
	v_sub_f32_e32 v80, 1.0, v82
	v_fma_f32 v78, v78, v80, v82
	v_sub_f32_e32 v80, 1.0, v83
	v_fmac_f32_e32 v83, v79, v80
	v_log_f32_e32 v76, v76
	v_log_f32_e32 v77, v77
	v_log_f32_e32 v78, v78
	v_log_f32_e32 v79, v83
	v_pk_mul_f32 v[76:77], v[76:77], s[96:97] op_sel_hi:[1,0]
	v_pk_mul_f32 v[78:79], v[78:79], s[96:97] op_sel_hi:[1,0]

.LBB0_220:
	v_cmp_ne_u32_e32 vcc, 3, v135
	s_and_saveexec_b64 s[8:9], vcc
	s_cbranch_execz .LBB0_222
	v_mov_b64_e32 v[80:81], v[148:149]
	v_mov_b64_e32 v[82:83], v[150:151]
	v_mul_f32_e32 v72, 0xbfb8aa3b, v72
	v_exp_f32_e32 v72, v72
	v_mul_f32_e32 v73, 0xbfb8aa3b, v73
	v_exp_f32_e32 v73, v73
	v_mul_f32_e32 v74, 0xbfb8aa3b, v74
	v_exp_f32_e32 v74, v74
	v_mul_f32_e32 v75, 0xbfb8aa3b, v75
	v_exp_f32_e32 v75, v75
	v_add_f32_e32 v72, 1.0, v72
	v_rcp_f32_e32 v72, v72
	v_add_f32_e32 v73, 1.0, v73
	v_rcp_f32_e32 v73, v73
	v_add_f32_e32 v74, 1.0, v74
	v_rcp_f32_e32 v74, v74
	v_add_f32_e32 v75, 1.0, v75
	v_rcp_f32_e32 v75, v75
	v_sub_f32_e32 v84, 1.0, v80
	v_fma_f32 v72, v72, v84, v80
	v_sub_f32_e32 v80, 1.0, v81
	v_fma_f32 v73, v73, v80, v81
	v_sub_f32_e32 v80, 1.0, v82
	v_fma_f32 v74, v74, v80, v82
	v_sub_f32_e32 v80, 1.0, v83
	v_fmac_f32_e32 v83, v75, v80
	v_log_f32_e32 v72, v72
	v_log_f32_e32 v73, v73
	v_log_f32_e32 v74, v74
	v_log_f32_e32 v75, v83
	v_pk_mul_f32 v[72:73], v[72:73], s[96:97] op_sel_hi:[1,0]
	v_pk_mul_f32 v[74:75], v[74:75], s[96:97] op_sel_hi:[1,0]

.LBB0_227:
	s_or_b64 exec, exec, s[2:3]
	v_add_u32_e32 v80, 48, v128
	v_ashrrev_i32_e32 v81, 31, v80
	v_cvt_pk_bf16_f32 v84, v72, v73
	v_lshl_add_u64 v[72:73], v[120:121], 0, v[80:81]
	v_lshlrev_b64 v[72:73], 12, v[72:73]
	v_cvt_pk_bf16_f32 v83, v78, v79
	v_cvt_pk_bf16_f32 v82, v76, v77
	v_cvt_pk_bf16_f32 v85, v74, v75
	v_lshl_add_u64 v[72:73], s[86:87], 0, v[72:73]
	v_permlane16_swap_b32_e32 v82, v84
	v_permlane16_swap_b32_e32 v83, v85
	v_lshl_add_u64 v[72:73], v[72:73], 0, v[176:177]
	global_store_dwordx4 v[72:73], v[82:85], off
	s_and_saveexec_b64 s[2:3], s[48:49]
	s_xor_b64 s[2:3], exec, s[2:3]
	s_cbranch_execz .LBB0_235
	v_cmp_ne_u32_e32 vcc, 3, v126
	s_and_saveexec_b64 s[8:9], vcc
	s_cbranch_execz .LBB0_230
	v_mov_b64_e32 v[72:73], v[152:153]
	v_mov_b64_e32 v[74:75], v[154:155]
	v_mul_f32_e32 v68, 0xbfb8aa3b, v68
	v_exp_f32_e32 v68, v68
	v_mul_f32_e32 v69, 0xbfb8aa3b, v69
	v_exp_f32_e32 v69, v69
	v_mul_f32_e32 v70, 0xbfb8aa3b, v70
	v_exp_f32_e32 v70, v70
	v_mul_f32_e32 v71, 0xbfb8aa3b, v71
	v_exp_f32_e32 v71, v71
	v_add_f32_e32 v68, 1.0, v68
	v_rcp_f32_e32 v68, v68
	v_add_f32_e32 v69, 1.0, v69
	v_rcp_f32_e32 v69, v69
	v_add_f32_e32 v70, 1.0, v70
	v_rcp_f32_e32 v70, v70
	v_add_f32_e32 v71, 1.0, v71
	v_rcp_f32_e32 v71, v71
	v_sub_f32_e32 v76, 1.0, v72
	v_fma_f32 v68, v68, v76, v72
	v_sub_f32_e32 v72, 1.0, v73
	v_fma_f32 v69, v69, v72, v73
	v_sub_f32_e32 v72, 1.0, v74
	v_fma_f32 v70, v70, v72, v74
	v_sub_f32_e32 v72, 1.0, v75
	v_fmac_f32_e32 v75, v71, v72
	v_log_f32_e32 v68, v68
	v_log_f32_e32 v69, v69
	v_log_f32_e32 v70, v70
	v_log_f32_e32 v71, v75
	v_pk_mul_f32 v[68:69], v[68:69], s[96:97] op_sel_hi:[1,0]
	v_pk_mul_f32 v[70:71], v[70:71], s[96:97] op_sel_hi:[1,0]

.LBB0_232:
	v_cmp_ne_u32_e32 vcc, 3, v127
	s_and_saveexec_b64 s[8:9], vcc
	s_cbranch_execz .LBB0_234
	v_mov_b64_e32 v[72:73], v[156:157]
	v_mov_b64_e32 v[74:75], v[158:159]
	v_mul_f32_e32 v64, 0xbfb8aa3b, v64
	v_exp_f32_e32 v64, v64
	v_mul_f32_e32 v65, 0xbfb8aa3b, v65
	v_exp_f32_e32 v65, v65
	v_mul_f32_e32 v66, 0xbfb8aa3b, v66
	v_exp_f32_e32 v66, v66
	v_mul_f32_e32 v67, 0xbfb8aa3b, v67
	v_exp_f32_e32 v67, v67
	v_add_f32_e32 v64, 1.0, v64
	v_rcp_f32_e32 v64, v64
	v_add_f32_e32 v65, 1.0, v65
	v_rcp_f32_e32 v65, v65
	v_add_f32_e32 v66, 1.0, v66
	v_rcp_f32_e32 v66, v66
	v_add_f32_e32 v67, 1.0, v67
	v_rcp_f32_e32 v67, v67
	v_sub_f32_e32 v76, 1.0, v72
	v_fma_f32 v64, v64, v76, v72
	v_sub_f32_e32 v72, 1.0, v73
	v_fma_f32 v65, v65, v72, v73
	v_sub_f32_e32 v72, 1.0, v74
	v_fma_f32 v66, v66, v72, v74
	v_sub_f32_e32 v72, 1.0, v75
	v_fmac_f32_e32 v75, v67, v72
	v_log_f32_e32 v64, v64
	v_log_f32_e32 v65, v65
	v_log_f32_e32 v66, v66
	v_log_f32_e32 v67, v75
	v_pk_mul_f32 v[64:65], v[64:65], s[96:97] op_sel_hi:[1,0]
	v_pk_mul_f32 v[66:67], v[66:67], s[96:97] op_sel_hi:[1,0]

.LBB0_239:
	s_or_b64 exec, exec, s[2:3]
	v_cvt_pk_bf16_f32 v72, v64, v65
	v_lshl_add_u64 v[64:65], v[112:113], 0, v[80:81]
	v_lshlrev_b64 v[64:65], 12, v[64:65]
	v_cvt_pk_bf16_f32 v71, v70, v71
	v_cvt_pk_bf16_f32 v70, v68, v69
	v_cvt_pk_bf16_f32 v73, v66, v67
	v_lshl_add_u64 v[64:65], s[86:87], 0, v[64:65]
	v_mov_b32_e32 v115, v177
	v_permlane16_swap_b32_e32 v70, v72
	v_permlane16_swap_b32_e32 v71, v73
	v_lshl_add_u64 v[64:65], v[64:65], 0, v[114:115]
	global_store_dwordx4 v[64:65], v[70:73], off
	s_and_saveexec_b64 s[2:3], s[44:45]
	s_xor_b64 s[2:3], exec, s[2:3]
	s_cbranch_execz .LBB0_247
	v_cmp_ne_u32_e32 vcc, 3, v133
	s_and_saveexec_b64 s[8:9], vcc
	s_cbranch_execz .LBB0_242
	v_mov_b64_e32 v[64:65], v[144:145]
	v_mov_b64_e32 v[66:67], v[146:147]
	v_mul_f32_e32 v60, 0xbfb8aa3b, v60
	v_exp_f32_e32 v60, v60
	v_mul_f32_e32 v61, 0xbfb8aa3b, v61
	v_exp_f32_e32 v61, v61
	v_mul_f32_e32 v62, 0xbfb8aa3b, v62
	v_exp_f32_e32 v62, v62
	v_mul_f32_e32 v63, 0xbfb8aa3b, v63
	v_exp_f32_e32 v63, v63
	v_add_f32_e32 v60, 1.0, v60
	v_rcp_f32_e32 v60, v60
	v_add_f32_e32 v61, 1.0, v61
	v_rcp_f32_e32 v61, v61
	v_add_f32_e32 v62, 1.0, v62
	v_rcp_f32_e32 v62, v62
	v_add_f32_e32 v63, 1.0, v63
	v_rcp_f32_e32 v63, v63
	v_sub_f32_e32 v68, 1.0, v64
	v_fma_f32 v60, v60, v68, v64
	v_sub_f32_e32 v64, 1.0, v65
	v_fma_f32 v61, v61, v64, v65
	v_sub_f32_e32 v64, 1.0, v66
	v_fma_f32 v62, v62, v64, v66
	v_sub_f32_e32 v64, 1.0, v67
	v_fmac_f32_e32 v67, v63, v64
	v_log_f32_e32 v60, v60
	v_log_f32_e32 v61, v61
	v_log_f32_e32 v62, v62
	v_log_f32_e32 v63, v67
	v_pk_mul_f32 v[60:61], v[60:61], s[96:97] op_sel_hi:[1,0]
	v_pk_mul_f32 v[62:63], v[62:63], s[96:97] op_sel_hi:[1,0]

.LBB0_244:
	v_cmp_ne_u32_e32 vcc, 3, v135
	s_and_saveexec_b64 s[8:9], vcc
	s_cbranch_execz .LBB0_246
	v_mov_b64_e32 v[64:65], v[148:149]
	v_mov_b64_e32 v[66:67], v[150:151]
	v_mul_f32_e32 v56, 0xbfb8aa3b, v56
	v_exp_f32_e32 v56, v56
	v_mul_f32_e32 v57, 0xbfb8aa3b, v57
	v_exp_f32_e32 v57, v57
	v_mul_f32_e32 v58, 0xbfb8aa3b, v58
	v_exp_f32_e32 v58, v58
	v_mul_f32_e32 v59, 0xbfb8aa3b, v59
	v_exp_f32_e32 v59, v59
	v_add_f32_e32 v56, 1.0, v56
	v_rcp_f32_e32 v56, v56
	v_add_f32_e32 v57, 1.0, v57
	v_rcp_f32_e32 v57, v57
	v_add_f32_e32 v58, 1.0, v58
	v_rcp_f32_e32 v58, v58
	v_add_f32_e32 v59, 1.0, v59
	v_rcp_f32_e32 v59, v59
	v_sub_f32_e32 v68, 1.0, v64
	v_fma_f32 v56, v56, v68, v64
	v_sub_f32_e32 v64, 1.0, v65
	v_fma_f32 v57, v57, v64, v65
	v_sub_f32_e32 v64, 1.0, v66
	v_fma_f32 v58, v58, v64, v66
	v_sub_f32_e32 v64, 1.0, v67
	v_fmac_f32_e32 v67, v59, v64
	v_log_f32_e32 v56, v56
	v_log_f32_e32 v57, v57
	v_log_f32_e32 v58, v58
	v_log_f32_e32 v59, v67
	v_pk_mul_f32 v[56:57], v[56:57], s[96:97] op_sel_hi:[1,0]
	v_pk_mul_f32 v[58:59], v[58:59], s[96:97] op_sel_hi:[1,0]

.LBB0_251:
	s_or_b64 exec, exec, s[2:3]
	v_add_u32_e32 v64, 64, v128
	v_ashrrev_i32_e32 v65, 31, v64
	v_cvt_pk_bf16_f32 v68, v56, v57
	v_lshl_add_u64 v[56:57], v[120:121], 0, v[64:65]
	v_lshlrev_b64 v[56:57], 12, v[56:57]
	v_cvt_pk_bf16_f32 v67, v62, v63
	v_cvt_pk_bf16_f32 v66, v60, v61
	v_cvt_pk_bf16_f32 v69, v58, v59
	v_lshl_add_u64 v[56:57], s[86:87], 0, v[56:57]
	v_permlane16_swap_b32_e32 v66, v68
	v_permlane16_swap_b32_e32 v67, v69
	v_lshl_add_u64 v[56:57], v[56:57], 0, v[176:177]
	global_store_dwordx4 v[56:57], v[66:69], off
	s_and_saveexec_b64 s[2:3], s[48:49]
	s_xor_b64 s[2:3], exec, s[2:3]
	s_cbranch_execz .LBB0_259
	v_cmp_ne_u32_e32 vcc, 3, v126
	s_and_saveexec_b64 s[8:9], vcc
	s_cbranch_execz .LBB0_254
	v_mov_b64_e32 v[56:57], v[152:153]
	v_mov_b64_e32 v[58:59], v[154:155]
	v_mul_f32_e32 v52, 0xbfb8aa3b, v52
	v_exp_f32_e32 v52, v52
	v_mul_f32_e32 v53, 0xbfb8aa3b, v53
	v_exp_f32_e32 v53, v53
	v_mul_f32_e32 v54, 0xbfb8aa3b, v54
	v_exp_f32_e32 v54, v54
	v_mul_f32_e32 v55, 0xbfb8aa3b, v55
	v_exp_f32_e32 v55, v55
	v_add_f32_e32 v52, 1.0, v52
	v_rcp_f32_e32 v52, v52
	v_add_f32_e32 v53, 1.0, v53
	v_rcp_f32_e32 v53, v53
	v_add_f32_e32 v54, 1.0, v54
	v_rcp_f32_e32 v54, v54
	v_add_f32_e32 v55, 1.0, v55
	v_rcp_f32_e32 v55, v55
	v_sub_f32_e32 v60, 1.0, v56
	v_fma_f32 v52, v52, v60, v56
	v_sub_f32_e32 v56, 1.0, v57
	v_fma_f32 v53, v53, v56, v57
	v_sub_f32_e32 v56, 1.0, v58
	v_fma_f32 v54, v54, v56, v58
	v_sub_f32_e32 v56, 1.0, v59
	v_fmac_f32_e32 v59, v55, v56
	v_log_f32_e32 v52, v52
	v_log_f32_e32 v53, v53
	v_log_f32_e32 v54, v54
	v_log_f32_e32 v55, v59
	v_pk_mul_f32 v[52:53], v[52:53], s[96:97] op_sel_hi:[1,0]
	v_pk_mul_f32 v[54:55], v[54:55], s[96:97] op_sel_hi:[1,0]

.LBB0_256:
	v_cmp_ne_u32_e32 vcc, 3, v127
	s_and_saveexec_b64 s[8:9], vcc
	s_cbranch_execz .LBB0_258
	v_mov_b64_e32 v[56:57], v[156:157]
	v_mov_b64_e32 v[58:59], v[158:159]
	v_mul_f32_e32 v48, 0xbfb8aa3b, v48
	v_exp_f32_e32 v48, v48
	v_mul_f32_e32 v49, 0xbfb8aa3b, v49
	v_exp_f32_e32 v49, v49
	v_mul_f32_e32 v50, 0xbfb8aa3b, v50
	v_exp_f32_e32 v50, v50
	v_mul_f32_e32 v51, 0xbfb8aa3b, v51
	v_exp_f32_e32 v51, v51
	v_add_f32_e32 v48, 1.0, v48
	v_rcp_f32_e32 v48, v48
	v_add_f32_e32 v49, 1.0, v49
	v_rcp_f32_e32 v49, v49
	v_add_f32_e32 v50, 1.0, v50
	v_rcp_f32_e32 v50, v50
	v_add_f32_e32 v51, 1.0, v51
	v_rcp_f32_e32 v51, v51
	v_sub_f32_e32 v60, 1.0, v56
	v_fma_f32 v48, v48, v60, v56
	v_sub_f32_e32 v56, 1.0, v57
	v_fma_f32 v49, v49, v56, v57
	v_sub_f32_e32 v56, 1.0, v58
	v_fma_f32 v50, v50, v56, v58
	v_sub_f32_e32 v56, 1.0, v59
	v_fmac_f32_e32 v59, v51, v56
	v_log_f32_e32 v48, v48
	v_log_f32_e32 v49, v49
	v_log_f32_e32 v50, v50
	v_log_f32_e32 v51, v59
	v_pk_mul_f32 v[48:49], v[48:49], s[96:97] op_sel_hi:[1,0]
	v_pk_mul_f32 v[50:51], v[50:51], s[96:97] op_sel_hi:[1,0]

.LBB0_263:
	s_or_b64 exec, exec, s[2:3]
	v_cvt_pk_bf16_f32 v56, v48, v49
	v_lshl_add_u64 v[48:49], v[112:113], 0, v[64:65]
	v_lshlrev_b64 v[48:49], 12, v[48:49]
	v_cvt_pk_bf16_f32 v55, v54, v55
	v_cvt_pk_bf16_f32 v54, v52, v53
	v_cvt_pk_bf16_f32 v57, v50, v51
	v_lshl_add_u64 v[48:49], s[86:87], 0, v[48:49]
	v_mov_b32_e32 v115, v177
	v_permlane16_swap_b32_e32 v54, v56
	v_permlane16_swap_b32_e32 v55, v57
	v_lshl_add_u64 v[48:49], v[48:49], 0, v[114:115]
	global_store_dwordx4 v[48:49], v[54:57], off
	s_and_saveexec_b64 s[2:3], s[44:45]
	s_xor_b64 s[2:3], exec, s[2:3]
	s_cbranch_execz .LBB0_271
	v_cmp_ne_u32_e32 vcc, 3, v133
	s_and_saveexec_b64 s[8:9], vcc
	s_cbranch_execz .LBB0_266
	v_mov_b64_e32 v[48:49], v[144:145]
	v_mov_b64_e32 v[50:51], v[146:147]
	v_mul_f32_e32 v44, 0xbfb8aa3b, v44
	v_exp_f32_e32 v44, v44
	v_mul_f32_e32 v45, 0xbfb8aa3b, v45
	v_exp_f32_e32 v45, v45
	v_mul_f32_e32 v46, 0xbfb8aa3b, v46
	v_exp_f32_e32 v46, v46
	v_mul_f32_e32 v47, 0xbfb8aa3b, v47
	v_exp_f32_e32 v47, v47
	v_add_f32_e32 v44, 1.0, v44
	v_rcp_f32_e32 v44, v44
	v_add_f32_e32 v45, 1.0, v45
	v_rcp_f32_e32 v45, v45
	v_add_f32_e32 v46, 1.0, v46
	v_rcp_f32_e32 v46, v46
	v_add_f32_e32 v47, 1.0, v47
	v_rcp_f32_e32 v47, v47
	v_sub_f32_e32 v52, 1.0, v48
	v_fma_f32 v44, v44, v52, v48
	v_sub_f32_e32 v48, 1.0, v49
	v_fma_f32 v45, v45, v48, v49
	v_sub_f32_e32 v48, 1.0, v50
	v_fma_f32 v46, v46, v48, v50
	v_sub_f32_e32 v48, 1.0, v51
	v_fmac_f32_e32 v51, v47, v48
	v_log_f32_e32 v44, v44
	v_log_f32_e32 v45, v45
	v_log_f32_e32 v46, v46
	v_log_f32_e32 v47, v51
	v_pk_mul_f32 v[44:45], v[44:45], s[96:97] op_sel_hi:[1,0]
	v_pk_mul_f32 v[46:47], v[46:47], s[96:97] op_sel_hi:[1,0]

.LBB0_268:
	v_cmp_ne_u32_e32 vcc, 3, v135
	s_and_saveexec_b64 s[8:9], vcc
	s_cbranch_execz .LBB0_270
	v_mov_b64_e32 v[48:49], v[148:149]
	v_mov_b64_e32 v[50:51], v[150:151]
	v_mul_f32_e32 v40, 0xbfb8aa3b, v40
	v_exp_f32_e32 v40, v40
	v_mul_f32_e32 v41, 0xbfb8aa3b, v41
	v_exp_f32_e32 v41, v41
	v_mul_f32_e32 v42, 0xbfb8aa3b, v42
	v_exp_f32_e32 v42, v42
	v_mul_f32_e32 v43, 0xbfb8aa3b, v43
	v_exp_f32_e32 v43, v43
	v_add_f32_e32 v40, 1.0, v40
	v_rcp_f32_e32 v40, v40
	v_add_f32_e32 v41, 1.0, v41
	v_rcp_f32_e32 v41, v41
	v_add_f32_e32 v42, 1.0, v42
	v_rcp_f32_e32 v42, v42
	v_add_f32_e32 v43, 1.0, v43
	v_rcp_f32_e32 v43, v43
	v_sub_f32_e32 v52, 1.0, v48
	v_fma_f32 v40, v40, v52, v48
	v_sub_f32_e32 v48, 1.0, v49
	v_fma_f32 v41, v41, v48, v49
	v_sub_f32_e32 v48, 1.0, v50
	v_fma_f32 v42, v42, v48, v50
	v_sub_f32_e32 v48, 1.0, v51
	v_fmac_f32_e32 v51, v43, v48
	v_log_f32_e32 v40, v40
	v_log_f32_e32 v41, v41
	v_log_f32_e32 v42, v42
	v_log_f32_e32 v43, v51
	v_pk_mul_f32 v[40:41], v[40:41], s[96:97] op_sel_hi:[1,0]
	v_pk_mul_f32 v[42:43], v[42:43], s[96:97] op_sel_hi:[1,0]

.LBB0_275:
	s_or_b64 exec, exec, s[2:3]
	v_add_u32_e32 v48, 0x50, v128
	v_ashrrev_i32_e32 v49, 31, v48
	v_cvt_pk_bf16_f32 v52, v40, v41
	v_lshl_add_u64 v[40:41], v[120:121], 0, v[48:49]
	v_lshlrev_b64 v[40:41], 12, v[40:41]
	v_cvt_pk_bf16_f32 v51, v46, v47
	v_cvt_pk_bf16_f32 v50, v44, v45
	v_cvt_pk_bf16_f32 v53, v42, v43
	v_lshl_add_u64 v[40:41], s[86:87], 0, v[40:41]
	v_permlane16_swap_b32_e32 v50, v52
	v_permlane16_swap_b32_e32 v51, v53
	v_lshl_add_u64 v[40:41], v[40:41], 0, v[176:177]
	global_store_dwordx4 v[40:41], v[50:53], off
	s_and_saveexec_b64 s[2:3], s[48:49]
	s_xor_b64 s[2:3], exec, s[2:3]
	s_cbranch_execz .LBB0_283
	v_cmp_ne_u32_e32 vcc, 3, v126
	s_and_saveexec_b64 s[8:9], vcc
	s_cbranch_execz .LBB0_278
	v_mov_b64_e32 v[40:41], v[152:153]
	v_mov_b64_e32 v[42:43], v[154:155]
	v_mul_f32_e32 v36, 0xbfb8aa3b, v36
	v_exp_f32_e32 v36, v36
	v_mul_f32_e32 v37, 0xbfb8aa3b, v37
	v_exp_f32_e32 v37, v37
	v_mul_f32_e32 v38, 0xbfb8aa3b, v38
	v_exp_f32_e32 v38, v38
	v_mul_f32_e32 v39, 0xbfb8aa3b, v39
	v_exp_f32_e32 v39, v39
	v_add_f32_e32 v36, 1.0, v36
	v_rcp_f32_e32 v36, v36
	v_add_f32_e32 v37, 1.0, v37
	v_rcp_f32_e32 v37, v37
	v_add_f32_e32 v38, 1.0, v38
	v_rcp_f32_e32 v38, v38
	v_add_f32_e32 v39, 1.0, v39
	v_rcp_f32_e32 v39, v39
	v_sub_f32_e32 v44, 1.0, v40
	v_fma_f32 v36, v36, v44, v40
	v_sub_f32_e32 v40, 1.0, v41
	v_fma_f32 v37, v37, v40, v41
	v_sub_f32_e32 v40, 1.0, v42
	v_fma_f32 v38, v38, v40, v42
	v_sub_f32_e32 v40, 1.0, v43
	v_fmac_f32_e32 v43, v39, v40
	v_log_f32_e32 v36, v36
	v_log_f32_e32 v37, v37
	v_log_f32_e32 v38, v38
	v_log_f32_e32 v39, v43
	v_pk_mul_f32 v[36:37], v[36:37], s[96:97] op_sel_hi:[1,0]
	v_pk_mul_f32 v[38:39], v[38:39], s[96:97] op_sel_hi:[1,0]

.LBB0_280:
	v_cmp_ne_u32_e32 vcc, 3, v127
	s_and_saveexec_b64 s[8:9], vcc
	s_cbranch_execz .LBB0_282
	v_mov_b64_e32 v[40:41], v[156:157]
	v_mov_b64_e32 v[42:43], v[158:159]
	v_mul_f32_e32 v32, 0xbfb8aa3b, v32
	v_exp_f32_e32 v32, v32
	v_mul_f32_e32 v33, 0xbfb8aa3b, v33
	v_exp_f32_e32 v33, v33
	v_mul_f32_e32 v34, 0xbfb8aa3b, v34
	v_exp_f32_e32 v34, v34
	v_mul_f32_e32 v35, 0xbfb8aa3b, v35
	v_exp_f32_e32 v35, v35
	v_add_f32_e32 v32, 1.0, v32
	v_rcp_f32_e32 v32, v32
	v_add_f32_e32 v33, 1.0, v33
	v_rcp_f32_e32 v33, v33
	v_add_f32_e32 v34, 1.0, v34
	v_rcp_f32_e32 v34, v34
	v_add_f32_e32 v35, 1.0, v35
	v_rcp_f32_e32 v35, v35
	v_sub_f32_e32 v44, 1.0, v40
	v_fma_f32 v32, v32, v44, v40
	v_sub_f32_e32 v40, 1.0, v41
	v_fma_f32 v33, v33, v40, v41
	v_sub_f32_e32 v40, 1.0, v42
	v_fma_f32 v34, v34, v40, v42
	v_sub_f32_e32 v40, 1.0, v43
	v_fmac_f32_e32 v43, v35, v40
	v_log_f32_e32 v32, v32
	v_log_f32_e32 v33, v33
	v_log_f32_e32 v34, v34
	v_log_f32_e32 v35, v43
	v_pk_mul_f32 v[32:33], v[32:33], s[96:97] op_sel_hi:[1,0]
	v_pk_mul_f32 v[34:35], v[34:35], s[96:97] op_sel_hi:[1,0]

.LBB0_287:
	s_or_b64 exec, exec, s[2:3]
	v_cvt_pk_bf16_f32 v40, v32, v33
	v_lshl_add_u64 v[32:33], v[112:113], 0, v[48:49]
	v_lshlrev_b64 v[32:33], 12, v[32:33]
	v_cvt_pk_bf16_f32 v39, v38, v39
	v_cvt_pk_bf16_f32 v38, v36, v37
	v_cvt_pk_bf16_f32 v41, v34, v35
	v_lshl_add_u64 v[32:33], s[86:87], 0, v[32:33]
	v_mov_b32_e32 v115, v177
	v_permlane16_swap_b32_e32 v38, v40
	v_permlane16_swap_b32_e32 v39, v41
	v_lshl_add_u64 v[32:33], v[32:33], 0, v[114:115]
	global_store_dwordx4 v[32:33], v[38:41], off
	s_and_saveexec_b64 s[2:3], s[44:45]
	s_xor_b64 s[2:3], exec, s[2:3]
	s_cbranch_execz .LBB0_295
	v_cmp_ne_u32_e32 vcc, 3, v133
	s_and_saveexec_b64 s[8:9], vcc
	s_cbranch_execz .LBB0_290
	v_mov_b64_e32 v[32:33], v[144:145]
	v_mov_b64_e32 v[34:35], v[146:147]
	v_mul_f32_e32 v28, 0xbfb8aa3b, v28
	v_exp_f32_e32 v28, v28
	v_mul_f32_e32 v29, 0xbfb8aa3b, v29
	v_exp_f32_e32 v29, v29
	v_mul_f32_e32 v30, 0xbfb8aa3b, v30
	v_exp_f32_e32 v30, v30
	v_mul_f32_e32 v31, 0xbfb8aa3b, v31
	v_exp_f32_e32 v31, v31
	v_add_f32_e32 v28, 1.0, v28
	v_rcp_f32_e32 v28, v28
	v_add_f32_e32 v29, 1.0, v29
	v_rcp_f32_e32 v29, v29
	v_add_f32_e32 v30, 1.0, v30
	v_rcp_f32_e32 v30, v30
	v_add_f32_e32 v31, 1.0, v31
	v_rcp_f32_e32 v31, v31
	v_sub_f32_e32 v36, 1.0, v32
	v_fma_f32 v28, v28, v36, v32
	v_sub_f32_e32 v32, 1.0, v33
	v_fma_f32 v29, v29, v32, v33
	v_sub_f32_e32 v32, 1.0, v34
	v_fma_f32 v30, v30, v32, v34
	v_sub_f32_e32 v32, 1.0, v35
	v_fmac_f32_e32 v35, v31, v32
	v_log_f32_e32 v28, v28
	v_log_f32_e32 v29, v29
	v_log_f32_e32 v30, v30
	v_log_f32_e32 v31, v35
	v_pk_mul_f32 v[28:29], v[28:29], s[96:97] op_sel_hi:[1,0]
	v_pk_mul_f32 v[30:31], v[30:31], s[96:97] op_sel_hi:[1,0]

.LBB0_292:
	v_cmp_ne_u32_e32 vcc, 3, v135
	s_and_saveexec_b64 s[8:9], vcc
	s_cbranch_execz .LBB0_294
	v_mov_b64_e32 v[32:33], v[148:149]
	v_mov_b64_e32 v[34:35], v[150:151]
	v_mul_f32_e32 v24, 0xbfb8aa3b, v24
	v_exp_f32_e32 v24, v24
	v_mul_f32_e32 v25, 0xbfb8aa3b, v25
	v_exp_f32_e32 v25, v25
	v_mul_f32_e32 v26, 0xbfb8aa3b, v26
	v_exp_f32_e32 v26, v26
	v_mul_f32_e32 v27, 0xbfb8aa3b, v27
	v_exp_f32_e32 v27, v27
	v_add_f32_e32 v24, 1.0, v24
	v_rcp_f32_e32 v24, v24
	v_add_f32_e32 v25, 1.0, v25
	v_rcp_f32_e32 v25, v25
	v_add_f32_e32 v26, 1.0, v26
	v_rcp_f32_e32 v26, v26
	v_add_f32_e32 v27, 1.0, v27
	v_rcp_f32_e32 v27, v27
	v_sub_f32_e32 v36, 1.0, v32
	v_fma_f32 v24, v24, v36, v32
	v_sub_f32_e32 v32, 1.0, v33
	v_fma_f32 v25, v25, v32, v33
	v_sub_f32_e32 v32, 1.0, v34
	v_fma_f32 v26, v26, v32, v34
	v_sub_f32_e32 v32, 1.0, v35
	v_fmac_f32_e32 v35, v27, v32
	v_log_f32_e32 v24, v24
	v_log_f32_e32 v25, v25
	v_log_f32_e32 v26, v26
	v_log_f32_e32 v27, v35
	v_pk_mul_f32 v[24:25], v[24:25], s[96:97] op_sel_hi:[1,0]
	v_pk_mul_f32 v[26:27], v[26:27], s[96:97] op_sel_hi:[1,0]

.LBB0_299:
	s_or_b64 exec, exec, s[2:3]
	v_add_u32_e32 v32, 0x60, v128
	v_ashrrev_i32_e32 v33, 31, v32
	v_cvt_pk_bf16_f32 v36, v24, v25
	v_lshl_add_u64 v[24:25], v[120:121], 0, v[32:33]
	v_lshlrev_b64 v[24:25], 12, v[24:25]
	v_cvt_pk_bf16_f32 v35, v30, v31
	v_cvt_pk_bf16_f32 v34, v28, v29
	v_cvt_pk_bf16_f32 v37, v26, v27
	v_lshl_add_u64 v[24:25], s[86:87], 0, v[24:25]
	v_permlane16_swap_b32_e32 v34, v36
	v_permlane16_swap_b32_e32 v35, v37
	v_lshl_add_u64 v[24:25], v[24:25], 0, v[176:177]
	global_store_dwordx4 v[24:25], v[34:37], off
	s_and_saveexec_b64 s[2:3], s[48:49]
	s_xor_b64 s[2:3], exec, s[2:3]
	s_cbranch_execz .LBB0_307
	v_cmp_ne_u32_e32 vcc, 3, v126
	s_and_saveexec_b64 s[8:9], vcc
	s_cbranch_execz .LBB0_302
	v_mov_b64_e32 v[24:25], v[152:153]
	v_mov_b64_e32 v[26:27], v[154:155]
	v_mul_f32_e32 v20, 0xbfb8aa3b, v20
	v_exp_f32_e32 v20, v20
	v_mul_f32_e32 v21, 0xbfb8aa3b, v21
	v_exp_f32_e32 v21, v21
	v_mul_f32_e32 v22, 0xbfb8aa3b, v22
	v_exp_f32_e32 v22, v22
	v_mul_f32_e32 v23, 0xbfb8aa3b, v23
	v_exp_f32_e32 v23, v23
	v_add_f32_e32 v20, 1.0, v20
	v_rcp_f32_e32 v20, v20
	v_add_f32_e32 v21, 1.0, v21
	v_rcp_f32_e32 v21, v21
	v_add_f32_e32 v22, 1.0, v22
	v_rcp_f32_e32 v22, v22
	v_add_f32_e32 v23, 1.0, v23
	v_rcp_f32_e32 v23, v23
	v_sub_f32_e32 v28, 1.0, v24
	v_fma_f32 v20, v20, v28, v24
	v_sub_f32_e32 v24, 1.0, v25
	v_fma_f32 v21, v21, v24, v25
	v_sub_f32_e32 v24, 1.0, v26
	v_fma_f32 v22, v22, v24, v26
	v_sub_f32_e32 v24, 1.0, v27
	v_fmac_f32_e32 v27, v23, v24
	v_log_f32_e32 v20, v20
	v_log_f32_e32 v21, v21
	v_log_f32_e32 v22, v22
	v_log_f32_e32 v23, v27
	v_pk_mul_f32 v[20:21], v[20:21], s[96:97] op_sel_hi:[1,0]
	v_pk_mul_f32 v[22:23], v[22:23], s[96:97] op_sel_hi:[1,0]

.LBB0_304:
	v_cmp_ne_u32_e32 vcc, 3, v127
	s_and_saveexec_b64 s[8:9], vcc
	s_cbranch_execz .LBB0_306
	v_mov_b64_e32 v[24:25], v[156:157]
	v_mov_b64_e32 v[26:27], v[158:159]
	v_mul_f32_e32 v16, 0xbfb8aa3b, v16
	v_exp_f32_e32 v16, v16
	v_mul_f32_e32 v17, 0xbfb8aa3b, v17
	v_exp_f32_e32 v17, v17
	v_mul_f32_e32 v18, 0xbfb8aa3b, v18
	v_exp_f32_e32 v18, v18
	v_mul_f32_e32 v19, 0xbfb8aa3b, v19
	v_exp_f32_e32 v19, v19
	v_add_f32_e32 v16, 1.0, v16
	v_rcp_f32_e32 v16, v16
	v_add_f32_e32 v17, 1.0, v17
	v_rcp_f32_e32 v17, v17
	v_add_f32_e32 v18, 1.0, v18
	v_rcp_f32_e32 v18, v18
	v_add_f32_e32 v19, 1.0, v19
	v_rcp_f32_e32 v19, v19
	v_sub_f32_e32 v28, 1.0, v24
	v_fma_f32 v16, v16, v28, v24
	v_sub_f32_e32 v24, 1.0, v25
	v_fma_f32 v17, v17, v24, v25
	v_sub_f32_e32 v24, 1.0, v26
	v_fma_f32 v18, v18, v24, v26
	v_sub_f32_e32 v24, 1.0, v27
	v_fmac_f32_e32 v27, v19, v24
	v_log_f32_e32 v16, v16
	v_log_f32_e32 v17, v17
	v_log_f32_e32 v18, v18
	v_log_f32_e32 v19, v27
	v_pk_mul_f32 v[16:17], v[16:17], s[96:97] op_sel_hi:[1,0]
	v_pk_mul_f32 v[18:19], v[18:19], s[96:97] op_sel_hi:[1,0]

.LBB0_311:
	s_or_b64 exec, exec, s[2:3]
	v_cvt_pk_bf16_f32 v24, v16, v17
	v_lshl_add_u64 v[16:17], v[112:113], 0, v[32:33]
	v_lshlrev_b64 v[16:17], 12, v[16:17]
	v_cvt_pk_bf16_f32 v23, v22, v23
	v_cvt_pk_bf16_f32 v22, v20, v21
	v_cvt_pk_bf16_f32 v25, v18, v19
	v_lshl_add_u64 v[16:17], s[86:87], 0, v[16:17]
	v_mov_b32_e32 v115, v177
	v_permlane16_swap_b32_e32 v22, v24
	v_permlane16_swap_b32_e32 v23, v25
	v_lshl_add_u64 v[16:17], v[16:17], 0, v[114:115]
	global_store_dwordx4 v[16:17], v[22:25], off
	s_and_saveexec_b64 s[2:3], s[44:45]
	s_xor_b64 s[2:3], exec, s[2:3]
	s_cbranch_execz .LBB0_319
	v_cmp_ne_u32_e32 vcc, 3, v133
	s_and_saveexec_b64 s[8:9], vcc
	s_cbranch_execz .LBB0_314
	v_mov_b64_e32 v[16:17], v[144:145]
	v_mov_b64_e32 v[18:19], v[146:147]
	v_mul_f32_e32 v12, 0xbfb8aa3b, v12
	v_exp_f32_e32 v12, v12
	v_mul_f32_e32 v13, 0xbfb8aa3b, v13
	v_exp_f32_e32 v13, v13
	v_mul_f32_e32 v14, 0xbfb8aa3b, v14
	v_exp_f32_e32 v14, v14
	v_mul_f32_e32 v15, 0xbfb8aa3b, v15
	v_exp_f32_e32 v15, v15
	v_add_f32_e32 v12, 1.0, v12
	v_rcp_f32_e32 v12, v12
	v_add_f32_e32 v13, 1.0, v13
	v_rcp_f32_e32 v13, v13
	v_add_f32_e32 v14, 1.0, v14
	v_rcp_f32_e32 v14, v14
	v_add_f32_e32 v15, 1.0, v15
	v_rcp_f32_e32 v15, v15
	v_sub_f32_e32 v20, 1.0, v16
	v_fma_f32 v12, v12, v20, v16
	v_sub_f32_e32 v16, 1.0, v17
	v_fma_f32 v13, v13, v16, v17
	v_sub_f32_e32 v16, 1.0, v18
	v_fma_f32 v14, v14, v16, v18
	v_sub_f32_e32 v16, 1.0, v19
	v_fmac_f32_e32 v19, v15, v16
	v_log_f32_e32 v12, v12
	v_log_f32_e32 v13, v13
	v_log_f32_e32 v14, v14
	v_log_f32_e32 v15, v19
	v_pk_mul_f32 v[12:13], v[12:13], s[96:97] op_sel_hi:[1,0]
	v_pk_mul_f32 v[14:15], v[14:15], s[96:97] op_sel_hi:[1,0]

.LBB0_316:
	v_cmp_ne_u32_e32 vcc, 3, v135
	s_and_saveexec_b64 s[8:9], vcc
	s_cbranch_execz .LBB0_318
	v_mov_b64_e32 v[16:17], v[148:149]
	v_mov_b64_e32 v[18:19], v[150:151]
	v_mul_f32_e32 v8, 0xbfb8aa3b, v8
	v_exp_f32_e32 v8, v8
	v_mul_f32_e32 v9, 0xbfb8aa3b, v9
	v_exp_f32_e32 v9, v9
	v_mul_f32_e32 v10, 0xbfb8aa3b, v10
	v_exp_f32_e32 v10, v10
	v_mul_f32_e32 v11, 0xbfb8aa3b, v11
	v_exp_f32_e32 v11, v11
	v_add_f32_e32 v8, 1.0, v8
	v_rcp_f32_e32 v8, v8
	v_add_f32_e32 v9, 1.0, v9
	v_rcp_f32_e32 v9, v9
	v_add_f32_e32 v10, 1.0, v10
	v_rcp_f32_e32 v10, v10
	v_add_f32_e32 v11, 1.0, v11
	v_rcp_f32_e32 v11, v11
	v_sub_f32_e32 v20, 1.0, v16
	v_fma_f32 v8, v8, v20, v16
	v_sub_f32_e32 v16, 1.0, v17
	v_fma_f32 v9, v9, v16, v17
	v_sub_f32_e32 v16, 1.0, v18
	v_fma_f32 v10, v10, v16, v18
	v_sub_f32_e32 v16, 1.0, v19
	v_fmac_f32_e32 v19, v11, v16
	v_log_f32_e32 v8, v8
	v_log_f32_e32 v9, v9
	v_log_f32_e32 v10, v10
	v_log_f32_e32 v11, v19
	v_pk_mul_f32 v[8:9], v[8:9], s[96:97] op_sel_hi:[1,0]
	v_pk_mul_f32 v[10:11], v[10:11], s[96:97] op_sel_hi:[1,0]

.LBB0_323:
	s_or_b64 exec, exec, s[2:3]
	v_add_u32_e32 v16, 0x70, v128
	v_ashrrev_i32_e32 v17, 31, v16
	v_cvt_pk_bf16_f32 v20, v8, v9
	v_lshl_add_u64 v[8:9], v[120:121], 0, v[16:17]
	v_lshlrev_b64 v[8:9], 12, v[8:9]
	v_cvt_pk_bf16_f32 v19, v14, v15
	v_cvt_pk_bf16_f32 v18, v12, v13
	v_cvt_pk_bf16_f32 v21, v10, v11
	v_lshl_add_u64 v[8:9], s[86:87], 0, v[8:9]
	v_permlane16_swap_b32_e32 v18, v20
	v_permlane16_swap_b32_e32 v19, v21
	v_lshl_add_u64 v[8:9], v[8:9], 0, v[176:177]
	global_store_dwordx4 v[8:9], v[18:21], off
	s_and_saveexec_b64 s[2:3], s[48:49]
	s_xor_b64 s[2:3], exec, s[2:3]
	s_cbranch_execz .LBB0_331
	v_cmp_ne_u32_e32 vcc, 3, v126
	s_and_saveexec_b64 s[8:9], vcc
	s_cbranch_execz .LBB0_326
	v_mov_b64_e32 v[8:9], v[152:153]
	v_mov_b64_e32 v[10:11], v[154:155]
	v_mul_f32_e32 v4, 0xbfb8aa3b, v4
	v_exp_f32_e32 v4, v4
	v_mul_f32_e32 v5, 0xbfb8aa3b, v5
	v_exp_f32_e32 v5, v5
	v_mul_f32_e32 v6, 0xbfb8aa3b, v6
	v_exp_f32_e32 v6, v6
	v_mul_f32_e32 v7, 0xbfb8aa3b, v7
	v_exp_f32_e32 v7, v7
	v_add_f32_e32 v4, 1.0, v4
	v_rcp_f32_e32 v4, v4
	v_add_f32_e32 v5, 1.0, v5
	v_rcp_f32_e32 v5, v5
	v_add_f32_e32 v6, 1.0, v6
	v_rcp_f32_e32 v6, v6
	v_add_f32_e32 v7, 1.0, v7
	v_rcp_f32_e32 v7, v7
	v_sub_f32_e32 v12, 1.0, v8
	v_fma_f32 v4, v4, v12, v8
	v_sub_f32_e32 v8, 1.0, v9
	v_fma_f32 v5, v5, v8, v9
	v_sub_f32_e32 v8, 1.0, v10
	v_fma_f32 v6, v6, v8, v10
	v_sub_f32_e32 v8, 1.0, v11
	v_fmac_f32_e32 v11, v7, v8
	v_log_f32_e32 v4, v4
	v_log_f32_e32 v5, v5
	v_log_f32_e32 v6, v6
	v_log_f32_e32 v7, v11
	v_pk_mul_f32 v[4:5], v[4:5], s[96:97] op_sel_hi:[1,0]
	v_pk_mul_f32 v[6:7], v[6:7], s[96:97] op_sel_hi:[1,0]

.LBB0_328:
	v_cmp_ne_u32_e32 vcc, 3, v127
	s_and_saveexec_b64 s[2:3], vcc
	s_cbranch_execz .LBB0_330
	v_mov_b64_e32 v[8:9], v[156:157]
	v_mov_b64_e32 v[10:11], v[158:159]
	v_mul_f32_e32 v0, 0xbfb8aa3b, v0
	v_exp_f32_e32 v0, v0
	v_mul_f32_e32 v1, 0xbfb8aa3b, v1
	v_exp_f32_e32 v1, v1
	v_mul_f32_e32 v2, 0xbfb8aa3b, v2
	v_exp_f32_e32 v2, v2
	v_mul_f32_e32 v3, 0xbfb8aa3b, v3
	v_exp_f32_e32 v3, v3
	v_add_f32_e32 v0, 1.0, v0
	v_rcp_f32_e32 v0, v0
	v_add_f32_e32 v1, 1.0, v1
	v_rcp_f32_e32 v1, v1
	v_add_f32_e32 v2, 1.0, v2
	v_rcp_f32_e32 v2, v2
	v_add_f32_e32 v3, 1.0, v3
	v_rcp_f32_e32 v3, v3
	v_sub_f32_e32 v12, 1.0, v8
	v_fma_f32 v0, v0, v12, v8
	v_sub_f32_e32 v8, 1.0, v9
	v_fma_f32 v1, v1, v8, v9
	v_sub_f32_e32 v8, 1.0, v10
	v_fma_f32 v2, v2, v8, v10
	v_sub_f32_e32 v8, 1.0, v11
	v_fmac_f32_e32 v11, v3, v8
	v_log_f32_e32 v0, v0
	v_log_f32_e32 v1, v1
	v_log_f32_e32 v2, v2
	v_log_f32_e32 v3, v11
	v_pk_mul_f32 v[0:1], v[0:1], s[96:97] op_sel_hi:[1,0]
	v_pk_mul_f32 v[2:3], v[2:3], s[96:97] op_sel_hi:[1,0]
